# stack: MLA loop x2 unroll with static LDS offsets + K/V staging loads without register moves (V to its own regs, K2 via saddr) + P2 mask-free interior tiles
# speedup vs baseline: 1.0045x; 1.0045x over previous
.Lf_entry:
	v_mov_b32_e32 v10, 0
	v_mov_b32_e32 v211, 0
	v_lshlrev_b32_e32 v249, 1, v198
.Lf_960:
	global_load_dwordx4 v[2:5], v[202:203], off
	global_load_dwordx4 v[192:195], v[200:201], off
	s_add_i32 s33, s24, 1
	s_and_saveexec_b64 s[44:45], s[0:1]
	s_cbranch_execz .Lf_962
	s_mul_i32 s6, s33, 0x1800
	s_lshl_b64 s[54:55], s[6:7], 1
	s_add_u32 s54, s42, s54
	s_addc_u32 s55, s43, s55
	global_load_dwordx4 v[6:9], v249, s[54:55]
.Lf_962:
	s_or_b64 exec, exec, s[44:45]
	ds_read_b128 v[12:15], v212
	ds_read_b128 v[80:83], v212 offset:32
	ds_read_b128 v[84:87], v212 offset:64
	ds_read_b128 v[88:91], v212 offset:96
	ds_read_b128 v[92:95], v212 offset:128
	ds_read_b128 v[96:99], v212 offset:160
	s_waitcnt lgkmcnt(5)
	v_mfma_f32_32x32x16_bf16 v[128:143], v[12:15], v[188:191], 0
	v_mfma_f32_32x32x16_bf16 v[112:127], v[12:15], v[176:179], 0
	ds_read_b128 v[12:15], v212 offset:6656
	ds_read_b128 v[216:219], v212 offset:6688
	ds_read_b128 v[220:223], v212 offset:6720
	ds_read_b128 v[224:227], v212 offset:6752
	ds_read_b128 v[228:231], v212 offset:6784
	ds_read_b128 v[232:235], v212 offset:6816
	s_waitcnt lgkmcnt(10)
	v_mfma_f32_32x32x16_bf16 v[128:143], v[80:83], v[184:187], v[128:143]
	v_mfma_f32_32x32x16_bf16 v[112:127], v[80:83], v[168:171], v[112:127]
	s_waitcnt lgkmcnt(9)
	v_mfma_f32_32x32x16_bf16 v[128:143], v[84:87], v[180:183], v[128:143]
	v_mfma_f32_32x32x16_bf16 v[112:127], v[84:87], v[164:167], v[112:127]
	s_waitcnt lgkmcnt(8)
	v_mfma_f32_32x32x16_bf16 v[128:143], v[88:91], v[172:175], v[128:143]
	v_mfma_f32_32x32x16_bf16 v[112:127], v[88:91], v[152:155], v[112:127]
	s_waitcnt lgkmcnt(7)
	v_mfma_f32_32x32x16_bf16 v[128:143], v[92:95], v[160:163], v[128:143]
	v_mfma_f32_32x32x16_bf16 v[112:127], v[92:95], v[148:151], v[112:127]
	s_waitcnt lgkmcnt(6)
	v_mfma_f32_32x32x16_bf16 v[128:143], v[96:99], v[156:159], v[128:143]
	v_mfma_f32_32x32x16_bf16 v[112:127], v[96:99], v[144:147], v[112:127]
	s_waitcnt lgkmcnt(5)
	v_mfma_f32_32x32x16_bf16 v[96:111], v[12:15], v[188:191], 0
	s_waitcnt lgkmcnt(4)
	v_mfma_f32_32x32x16_bf16 v[96:111], v[216:219], v[184:187], v[96:111]
	v_mfma_f32_32x32x16_bf16 v[80:95], v[12:15], v[176:179], 0
	s_waitcnt lgkmcnt(3)
	v_mfma_f32_32x32x16_bf16 v[96:111], v[220:223], v[180:183], v[96:111]
	v_mfma_f32_32x32x16_bf16 v[80:95], v[216:219], v[168:171], v[80:95]
	s_waitcnt lgkmcnt(2)
	v_mfma_f32_32x32x16_bf16 v[96:111], v[224:227], v[172:175], v[96:111]
	v_mfma_f32_32x32x16_bf16 v[80:95], v[220:223], v[164:167], v[80:95]
	s_waitcnt lgkmcnt(1)
	v_mfma_f32_32x32x16_bf16 v[96:111], v[228:231], v[160:163], v[96:111]
	v_mfma_f32_32x32x16_bf16 v[80:95], v[224:227], v[152:155], v[80:95]
	s_waitcnt lgkmcnt(0)
	v_mfma_f32_32x32x16_bf16 v[96:111], v[232:235], v[156:159], v[96:111]
	v_mfma_f32_32x32x16_bf16 v[80:95], v[228:231], v[148:151], v[80:95]
	v_mfma_f32_32x32x16_bf16 v[80:95], v[232:235], v[144:147], v[80:95]
	v_exp_f32_e32 v11, v128
	v_exp_f32_e32 v12, v129
	v_exp_f32_e32 v13, v130
	v_exp_f32_e32 v14, v131
	v_exp_f32_e32 v15, v132
	v_exp_f32_e32 v128, v133
	v_exp_f32_e32 v129, v134
	v_exp_f32_e32 v130, v135
	v_exp_f32_e32 v131, v136
	v_exp_f32_e32 v132, v137
	v_exp_f32_e32 v133, v138
	v_exp_f32_e32 v135, v140
	v_exp_f32_e32 v136, v141
	v_exp_f32_e32 v137, v142
	v_exp_f32_e32 v138, v143
	v_exp_f32_e32 v112, v112
	v_exp_f32_e32 v113, v113
	v_exp_f32_e32 v114, v114
	v_exp_f32_e32 v115, v115
	v_exp_f32_e32 v116, v116
	v_exp_f32_e32 v117, v117
	v_exp_f32_e32 v118, v118
	v_exp_f32_e32 v119, v119
	v_cvt_pk_bf16_f32 v140, v11, v12
	v_cvt_pk_bf16_f32 v141, v13, v14
	v_cvt_pk_bf16_f32 v142, v15, v128
	v_cvt_pk_bf16_f32 v143, v129, v130
	v_cvt_pk_bf16_f32 v216, v112, v113
	v_cvt_pk_bf16_f32 v217, v114, v115
	v_cvt_pk_bf16_f32 v218, v116, v117
	v_cvt_pk_bf16_f32 v219, v118, v119
	ds_read_b128 v[220:223], v210 offset:26624
	ds_read_b128 v[224:227], v210 offset:31232
	v_exp_f32_e32 v134, v139
	v_exp_f32_e32 v120, v120
	s_waitcnt lgkmcnt(1)
	v_mfma_f32_32x32x16_bf16 v[64:79], v[220:223], v[140:143], v[64:79]
	v_exp_f32_e32 v121, v121
	v_exp_f32_e32 v122, v122
	v_exp_f32_e32 v123, v123
	v_exp_f32_e32 v124, v124
	v_exp_f32_e32 v125, v125
	v_exp_f32_e32 v126, v126
	v_exp_f32_e32 v127, v127
	v_mfma_f32_32x32x16_bf16 v[32:47], v[220:223], v[216:219], v[32:47]
	v_cvt_pk_bf16_f32 v220, v131, v132
	v_cvt_pk_bf16_f32 v221, v133, v134
	v_cvt_pk_bf16_f32 v222, v135, v136
	v_cvt_pk_bf16_f32 v223, v137, v138
	v_cvt_pk_bf16_f32 v228, v120, v121
	v_cvt_pk_bf16_f32 v229, v122, v123
	v_cvt_pk_bf16_f32 v230, v124, v125
	v_cvt_pk_bf16_f32 v231, v126, v127
	ds_read_b128 v[232:235], v210 offset:26656
	s_waitcnt lgkmcnt(1)
	v_mfma_f32_32x32x16_bf16 v[16:31], v[224:227], v[216:219], v[16:31]
	ds_read_b128 v[216:219], v210 offset:31264
	v_exp_f32_e32 v237, v106
	v_exp_f32_e32 v106, v81
	v_exp_f32_e32 v139, v82
	v_mfma_f32_32x32x16_bf16 v[48:63], v[224:227], v[140:143], v[48:63]
	v_exp_f32_e32 v140, v83
	v_exp_f32_e32 v141, v84
	v_exp_f32_e32 v142, v85
	v_exp_f32_e32 v143, v86
	v_exp_f32_e32 v96, v96
	v_exp_f32_e32 v97, v97
	v_exp_f32_e32 v98, v98
	v_exp_f32_e32 v99, v99
	v_exp_f32_e32 v100, v100
	v_exp_f32_e32 v101, v101
	v_exp_f32_e32 v102, v102
	v_exp_f32_e32 v103, v103
	v_exp_f32_e32 v80, v80
	s_waitcnt lgkmcnt(1)
	v_mfma_f32_32x32x16_bf16 v[64:79], v[232:235], v[220:223], v[64:79]
	v_exp_f32_e32 v87, v87
	v_mfma_f32_32x32x16_bf16 v[32:47], v[232:235], v[228:231], v[32:47]
	s_waitcnt lgkmcnt(0)
	v_mfma_f32_32x32x16_bf16 v[48:63], v[216:219], v[220:223], v[48:63]
	v_cvt_pk_bf16_f32 v220, v96, v97
	v_cvt_pk_bf16_f32 v221, v98, v99
	v_cvt_pk_bf16_f32 v222, v100, v101
	v_cvt_pk_bf16_f32 v223, v102, v103
	v_cvt_pk_bf16_f32 v224, v80, v106
	v_cvt_pk_bf16_f32 v225, v139, v140
	v_cvt_pk_bf16_f32 v226, v141, v142
	v_cvt_pk_bf16_f32 v227, v143, v87
	ds_read_b128 v[232:235], v210 offset:26688
	v_mfma_f32_32x32x16_bf16 v[16:31], v[216:219], v[228:231], v[16:31]
	ds_read_b128 v[216:219], v210 offset:31296
	v_exp_f32_e32 v104, v104
	v_exp_f32_e32 v105, v105
	v_exp_f32_e32 v82, v107
	s_waitcnt lgkmcnt(1)
	v_mfma_f32_32x32x16_bf16 v[64:79], v[232:235], v[220:223], v[64:79]
	v_exp_f32_e32 v83, v108
	v_exp_f32_e32 v84, v109
	v_exp_f32_e32 v85, v110
	v_exp_f32_e32 v86, v111
	v_exp_f32_e32 v88, v88
	v_exp_f32_e32 v89, v89
	v_exp_f32_e32 v90, v90
	v_mfma_f32_32x32x16_bf16 v[32:47], v[232:235], v[224:227], v[32:47]
	v_exp_f32_e32 v91, v91
	v_exp_f32_e32 v92, v92
	v_exp_f32_e32 v93, v93
	v_exp_f32_e32 v94, v94
	v_exp_f32_e32 v95, v95
	v_cvt_pk_bf16_f32 v108, v104, v105
	v_cvt_pk_bf16_f32 v109, v237, v82
	s_waitcnt lgkmcnt(0)
	v_mfma_f32_32x32x16_bf16 v[48:63], v[216:219], v[220:223], v[48:63]
	v_cvt_pk_bf16_f32 v110, v83, v84
	v_cvt_pk_bf16_f32 v111, v85, v86
	v_mfma_f32_32x32x16_bf16 v[16:31], v[216:219], v[224:227], v[16:31]
	v_cvt_pk_bf16_f32 v216, v88, v89
	v_cvt_pk_bf16_f32 v217, v90, v91
	v_cvt_pk_bf16_f32 v218, v92, v93
	v_cvt_pk_bf16_f32 v219, v94, v95
	ds_read_b128 v[220:223], v210 offset:26720
	ds_read_b128 v[224:227], v210 offset:31328
	s_waitcnt vmcnt(1)
	ds_write_b128 v213, v[2:5] offset:13312
	s_waitcnt lgkmcnt(2)
	v_mfma_f32_32x32x16_bf16 v[64:79], v[220:223], v[108:111], v[64:79]
	v_mfma_f32_32x32x16_bf16 v[32:47], v[220:223], v[216:219], v[32:47]
	s_waitcnt lgkmcnt(1)
	v_mfma_f32_32x32x16_bf16 v[48:63], v[224:227], v[108:111], v[48:63]
	v_mfma_f32_32x32x16_bf16 v[16:31], v[224:227], v[216:219], v[16:31]
	s_and_saveexec_b64 s[44:45], s[0:1]
	s_cbranch_execz .Lf_966
	s_waitcnt vmcnt(0)
	ds_write_b128 v214, v[6:9] offset:13312
.Lf_966:
	s_or_b64 exec, exec, s[44:45]
	s_waitcnt vmcnt(0)
	ds_write_b128 v215, v[192:195] offset:35840
	v_pk_add_f32 v[244:245], v[88:89], v[90:91]
	v_pk_add_f32 v[246:247], v[92:93], v[94:95]
	v_pk_add_f32 v[244:245], v[244:245], v[112:113]
	v_pk_add_f32 v[246:247], v[246:247], v[114:115]
	v_pk_add_f32 v[244:245], v[244:245], v[116:117]
	v_pk_add_f32 v[246:247], v[246:247], v[118:119]
	v_pk_add_f32 v[244:245], v[244:245], v[120:121]
	v_pk_add_f32 v[246:247], v[246:247], v[122:123]
	v_pk_add_f32 v[244:245], v[244:245], v[124:125]
	v_pk_add_f32 v[246:247], v[246:247], v[126:127]
	v_pk_add_f32 v[244:245], v[244:245], v[140:141]
	v_pk_add_f32 v[246:247], v[246:247], v[142:143]
	v_pk_add_f32 v[244:245], v[244:245], v[246:247]
	v_add_f32_e32 v248, v244, v245
	v_add_f32_e32 v248, v80, v248
	v_add_f32_e32 v248, v87, v248
	v_add_f32_e32 v248, v106, v248
	v_add_f32_e32 v248, v139, v248
	v_add_f32_e32 v206, v206, v248
	v_pk_add_f32 v[244:245], v[12:13], v[14:15]
	v_pk_add_f32 v[246:247], v[82:83], v[84:85]
	v_pk_add_f32 v[244:245], v[244:245], v[96:97]
	v_pk_add_f32 v[246:247], v[246:247], v[98:99]
	v_pk_add_f32 v[244:245], v[244:245], v[100:101]
	v_pk_add_f32 v[246:247], v[246:247], v[102:103]
	v_pk_add_f32 v[244:245], v[244:245], v[104:105]
	v_pk_add_f32 v[246:247], v[246:247], v[128:129]
	v_pk_add_f32 v[244:245], v[244:245], v[130:131]
	v_pk_add_f32 v[246:247], v[246:247], v[132:133]
	v_pk_add_f32 v[244:245], v[244:245], v[134:135]
	v_pk_add_f32 v[246:247], v[246:247], v[136:137]
	v_pk_add_f32 v[244:245], v[244:245], v[246:247]
	v_add_f32_e32 v248, v244, v245
	v_add_f32_e32 v248, v11, v248
	v_add_f32_e32 v248, v86, v248
	v_add_f32_e32 v248, v138, v248
	v_add_f32_e32 v248, v237, v248
	v_add_f32_e32 v0, v0, v248
	v_lshl_add_u64 v[200:201], v[200:201], 0, s[10:11]
	s_cmp_eq_u32 s33, 63
	v_lshl_add_u64 v[202:203], v[202:203], 0, s[12:13]
	s_waitcnt lgkmcnt(0)
	s_barrier
	s_cbranch_scc1 .LBB0_970
	global_load_dwordx4 v[2:5], v[202:203], off
	global_load_dwordx4 v[192:195], v[200:201], off
	s_add_i32 s33, s33, 1
	s_and_saveexec_b64 s[44:45], s[0:1]
	s_cbranch_execz .Lf_962o
	s_mul_i32 s6, s33, 0x1800
	s_lshl_b64 s[54:55], s[6:7], 1
	s_add_u32 s54, s42, s54
	s_addc_u32 s55, s43, s55
	global_load_dwordx4 v[6:9], v249, s[54:55]
.Lf_962o:
	s_or_b64 exec, exec, s[44:45]
	ds_read_b128 v[12:15], v212 offset:13312
	ds_read_b128 v[80:83], v212 offset:13344
	ds_read_b128 v[84:87], v212 offset:13376
	ds_read_b128 v[88:91], v212 offset:13408
	ds_read_b128 v[92:95], v212 offset:13440
	ds_read_b128 v[96:99], v212 offset:13472
	s_waitcnt lgkmcnt(5)
	v_mfma_f32_32x32x16_bf16 v[128:143], v[12:15], v[188:191], 0
	v_mfma_f32_32x32x16_bf16 v[112:127], v[12:15], v[176:179], 0
	ds_read_b128 v[12:15], v212 offset:19968
	ds_read_b128 v[216:219], v212 offset:20000
	ds_read_b128 v[220:223], v212 offset:20032
	ds_read_b128 v[224:227], v212 offset:20064
	ds_read_b128 v[228:231], v212 offset:20096
	ds_read_b128 v[232:235], v212 offset:20128
	s_waitcnt lgkmcnt(10)
	v_mfma_f32_32x32x16_bf16 v[128:143], v[80:83], v[184:187], v[128:143]
	v_mfma_f32_32x32x16_bf16 v[112:127], v[80:83], v[168:171], v[112:127]
	s_waitcnt lgkmcnt(9)
	v_mfma_f32_32x32x16_bf16 v[128:143], v[84:87], v[180:183], v[128:143]
	v_mfma_f32_32x32x16_bf16 v[112:127], v[84:87], v[164:167], v[112:127]
	s_waitcnt lgkmcnt(8)
	v_mfma_f32_32x32x16_bf16 v[128:143], v[88:91], v[172:175], v[128:143]
	v_mfma_f32_32x32x16_bf16 v[112:127], v[88:91], v[152:155], v[112:127]
	s_waitcnt lgkmcnt(7)
	v_mfma_f32_32x32x16_bf16 v[128:143], v[92:95], v[160:163], v[128:143]
	v_mfma_f32_32x32x16_bf16 v[112:127], v[92:95], v[148:151], v[112:127]
	s_waitcnt lgkmcnt(6)
	v_mfma_f32_32x32x16_bf16 v[128:143], v[96:99], v[156:159], v[128:143]
	v_mfma_f32_32x32x16_bf16 v[112:127], v[96:99], v[144:147], v[112:127]
	s_waitcnt lgkmcnt(5)
	v_mfma_f32_32x32x16_bf16 v[96:111], v[12:15], v[188:191], 0
	s_waitcnt lgkmcnt(4)
	v_mfma_f32_32x32x16_bf16 v[96:111], v[216:219], v[184:187], v[96:111]
	v_mfma_f32_32x32x16_bf16 v[80:95], v[12:15], v[176:179], 0
	s_waitcnt lgkmcnt(3)
	v_mfma_f32_32x32x16_bf16 v[96:111], v[220:223], v[180:183], v[96:111]
	v_mfma_f32_32x32x16_bf16 v[80:95], v[216:219], v[168:171], v[80:95]
	s_waitcnt lgkmcnt(2)
	v_mfma_f32_32x32x16_bf16 v[96:111], v[224:227], v[172:175], v[96:111]
	v_mfma_f32_32x32x16_bf16 v[80:95], v[220:223], v[164:167], v[80:95]
	s_waitcnt lgkmcnt(1)
	v_mfma_f32_32x32x16_bf16 v[96:111], v[228:231], v[160:163], v[96:111]
	v_mfma_f32_32x32x16_bf16 v[80:95], v[224:227], v[152:155], v[80:95]
	s_waitcnt lgkmcnt(0)
	v_mfma_f32_32x32x16_bf16 v[96:111], v[232:235], v[156:159], v[96:111]
	v_mfma_f32_32x32x16_bf16 v[80:95], v[228:231], v[148:151], v[80:95]
	v_mfma_f32_32x32x16_bf16 v[80:95], v[232:235], v[144:147], v[80:95]
	v_exp_f32_e32 v11, v128
	v_exp_f32_e32 v12, v129
	v_exp_f32_e32 v13, v130
	v_exp_f32_e32 v14, v131
	v_exp_f32_e32 v15, v132
	v_exp_f32_e32 v128, v133
	v_exp_f32_e32 v129, v134
	v_exp_f32_e32 v130, v135
	v_exp_f32_e32 v131, v136
	v_exp_f32_e32 v132, v137
	v_exp_f32_e32 v133, v138
	v_exp_f32_e32 v135, v140
	v_exp_f32_e32 v136, v141
	v_exp_f32_e32 v137, v142
	v_exp_f32_e32 v138, v143
	v_exp_f32_e32 v112, v112
	v_exp_f32_e32 v113, v113
	v_exp_f32_e32 v114, v114
	v_exp_f32_e32 v115, v115
	v_exp_f32_e32 v116, v116
	v_exp_f32_e32 v117, v117
	v_exp_f32_e32 v118, v118
	v_exp_f32_e32 v119, v119
	v_cvt_pk_bf16_f32 v140, v11, v12
	v_cvt_pk_bf16_f32 v141, v13, v14
	v_cvt_pk_bf16_f32 v142, v15, v128
	v_cvt_pk_bf16_f32 v143, v129, v130
	v_cvt_pk_bf16_f32 v216, v112, v113
	v_cvt_pk_bf16_f32 v217, v114, v115
	v_cvt_pk_bf16_f32 v218, v116, v117
	v_cvt_pk_bf16_f32 v219, v118, v119
	ds_read_b128 v[220:223], v210 offset:35840
	ds_read_b128 v[224:227], v210 offset:40448
	v_exp_f32_e32 v134, v139
	v_exp_f32_e32 v120, v120
	s_waitcnt lgkmcnt(1)
	v_mfma_f32_32x32x16_bf16 v[64:79], v[220:223], v[140:143], v[64:79]
	v_exp_f32_e32 v121, v121
	v_exp_f32_e32 v122, v122
	v_exp_f32_e32 v123, v123
	v_exp_f32_e32 v124, v124
	v_exp_f32_e32 v125, v125
	v_exp_f32_e32 v126, v126
	v_exp_f32_e32 v127, v127
	v_mfma_f32_32x32x16_bf16 v[32:47], v[220:223], v[216:219], v[32:47]
	v_cvt_pk_bf16_f32 v220, v131, v132
	v_cvt_pk_bf16_f32 v221, v133, v134
	v_cvt_pk_bf16_f32 v222, v135, v136
	v_cvt_pk_bf16_f32 v223, v137, v138
	v_cvt_pk_bf16_f32 v228, v120, v121
	v_cvt_pk_bf16_f32 v229, v122, v123
	v_cvt_pk_bf16_f32 v230, v124, v125
	v_cvt_pk_bf16_f32 v231, v126, v127
	ds_read_b128 v[232:235], v210 offset:35872
	s_waitcnt lgkmcnt(1)
	v_mfma_f32_32x32x16_bf16 v[16:31], v[224:227], v[216:219], v[16:31]
	ds_read_b128 v[216:219], v210 offset:40480
	v_exp_f32_e32 v237, v106
	v_exp_f32_e32 v106, v81
	v_exp_f32_e32 v139, v82
	v_mfma_f32_32x32x16_bf16 v[48:63], v[224:227], v[140:143], v[48:63]
	v_exp_f32_e32 v140, v83
	v_exp_f32_e32 v141, v84
	v_exp_f32_e32 v142, v85
	v_exp_f32_e32 v143, v86
	v_exp_f32_e32 v96, v96
	v_exp_f32_e32 v97, v97
	v_exp_f32_e32 v98, v98
	v_exp_f32_e32 v99, v99
	v_exp_f32_e32 v100, v100
	v_exp_f32_e32 v101, v101
	v_exp_f32_e32 v102, v102
	v_exp_f32_e32 v103, v103
	v_exp_f32_e32 v80, v80
	s_waitcnt lgkmcnt(1)
	v_mfma_f32_32x32x16_bf16 v[64:79], v[232:235], v[220:223], v[64:79]
	v_exp_f32_e32 v87, v87
	v_mfma_f32_32x32x16_bf16 v[32:47], v[232:235], v[228:231], v[32:47]
	s_waitcnt lgkmcnt(0)
	v_mfma_f32_32x32x16_bf16 v[48:63], v[216:219], v[220:223], v[48:63]
	v_cvt_pk_bf16_f32 v220, v96, v97
	v_cvt_pk_bf16_f32 v221, v98, v99
	v_cvt_pk_bf16_f32 v222, v100, v101
	v_cvt_pk_bf16_f32 v223, v102, v103
	v_cvt_pk_bf16_f32 v224, v80, v106
	v_cvt_pk_bf16_f32 v225, v139, v140
	v_cvt_pk_bf16_f32 v226, v141, v142
	v_cvt_pk_bf16_f32 v227, v143, v87
	ds_read_b128 v[232:235], v210 offset:35904
	v_mfma_f32_32x32x16_bf16 v[16:31], v[216:219], v[228:231], v[16:31]
	ds_read_b128 v[216:219], v210 offset:40512
	v_exp_f32_e32 v104, v104
	v_exp_f32_e32 v105, v105
	v_exp_f32_e32 v82, v107
	s_waitcnt lgkmcnt(1)
	v_mfma_f32_32x32x16_bf16 v[64:79], v[232:235], v[220:223], v[64:79]
	v_exp_f32_e32 v83, v108
	v_exp_f32_e32 v84, v109
	v_exp_f32_e32 v85, v110
	v_exp_f32_e32 v86, v111
	v_exp_f32_e32 v88, v88
	v_exp_f32_e32 v89, v89
	v_exp_f32_e32 v90, v90
	v_mfma_f32_32x32x16_bf16 v[32:47], v[232:235], v[224:227], v[32:47]
	v_exp_f32_e32 v91, v91
	v_exp_f32_e32 v92, v92
	v_exp_f32_e32 v93, v93
	v_exp_f32_e32 v94, v94
	v_exp_f32_e32 v95, v95
	v_cvt_pk_bf16_f32 v108, v104, v105
	v_cvt_pk_bf16_f32 v109, v237, v82
	s_waitcnt lgkmcnt(0)
	v_mfma_f32_32x32x16_bf16 v[48:63], v[216:219], v[220:223], v[48:63]
	v_cvt_pk_bf16_f32 v110, v83, v84
	v_cvt_pk_bf16_f32 v111, v85, v86
	v_mfma_f32_32x32x16_bf16 v[16:31], v[216:219], v[224:227], v[16:31]
	v_cvt_pk_bf16_f32 v216, v88, v89
	v_cvt_pk_bf16_f32 v217, v90, v91
	v_cvt_pk_bf16_f32 v218, v92, v93
	v_cvt_pk_bf16_f32 v219, v94, v95
	ds_read_b128 v[220:223], v210 offset:35936
	ds_read_b128 v[224:227], v210 offset:40544
	s_waitcnt vmcnt(1)
	ds_write_b128 v213, v[2:5]
	s_waitcnt lgkmcnt(2)
	v_mfma_f32_32x32x16_bf16 v[64:79], v[220:223], v[108:111], v[64:79]
	v_mfma_f32_32x32x16_bf16 v[32:47], v[220:223], v[216:219], v[32:47]
	s_waitcnt lgkmcnt(1)
	v_mfma_f32_32x32x16_bf16 v[48:63], v[224:227], v[108:111], v[48:63]
	v_mfma_f32_32x32x16_bf16 v[16:31], v[224:227], v[216:219], v[16:31]
	s_and_saveexec_b64 s[44:45], s[0:1]
	s_cbranch_execz .Lf_966o
	s_waitcnt vmcnt(0)
	ds_write_b128 v214, v[6:9]
.Lf_966o:
	s_or_b64 exec, exec, s[44:45]
	s_waitcnt vmcnt(0)
	ds_write_b128 v215, v[192:195] offset:26624
	v_pk_add_f32 v[244:245], v[88:89], v[90:91]
	v_pk_add_f32 v[246:247], v[92:93], v[94:95]
	v_pk_add_f32 v[244:245], v[244:245], v[112:113]
	v_pk_add_f32 v[246:247], v[246:247], v[114:115]
	v_pk_add_f32 v[244:245], v[244:245], v[116:117]
	v_pk_add_f32 v[246:247], v[246:247], v[118:119]
	v_pk_add_f32 v[244:245], v[244:245], v[120:121]
	v_pk_add_f32 v[246:247], v[246:247], v[122:123]
	v_pk_add_f32 v[244:245], v[244:245], v[124:125]
	v_pk_add_f32 v[246:247], v[246:247], v[126:127]
	v_pk_add_f32 v[244:245], v[244:245], v[140:141]
	v_pk_add_f32 v[246:247], v[246:247], v[142:143]
	v_pk_add_f32 v[244:245], v[244:245], v[246:247]
	v_add_f32_e32 v248, v244, v245
	v_add_f32_e32 v248, v80, v248
	v_add_f32_e32 v248, v87, v248
	v_add_f32_e32 v248, v106, v248
	v_add_f32_e32 v248, v139, v248
	v_add_f32_e32 v206, v206, v248
	v_pk_add_f32 v[244:245], v[12:13], v[14:15]
	v_pk_add_f32 v[246:247], v[82:83], v[84:85]
	v_pk_add_f32 v[244:245], v[244:245], v[96:97]
	v_pk_add_f32 v[246:247], v[246:247], v[98:99]
	v_pk_add_f32 v[244:245], v[244:245], v[100:101]
	v_pk_add_f32 v[246:247], v[246:247], v[102:103]
	v_pk_add_f32 v[244:245], v[244:245], v[104:105]
	v_pk_add_f32 v[246:247], v[246:247], v[128:129]
	v_pk_add_f32 v[244:245], v[244:245], v[130:131]
	v_pk_add_f32 v[246:247], v[246:247], v[132:133]
	v_pk_add_f32 v[244:245], v[244:245], v[134:135]
	v_pk_add_f32 v[246:247], v[246:247], v[136:137]
	v_pk_add_f32 v[244:245], v[244:245], v[246:247]
	v_add_f32_e32 v248, v244, v245
	v_add_f32_e32 v248, v11, v248
	v_add_f32_e32 v248, v86, v248
	v_add_f32_e32 v248, v138, v248
	v_add_f32_e32 v248, v237, v248
	v_add_f32_e32 v0, v0, v248
	v_lshl_add_u64 v[200:201], v[200:201], 0, s[10:11]
	v_lshl_add_u64 v[202:203], v[202:203], 0, s[12:13]
	s_waitcnt lgkmcnt(0)
	s_barrier
	s_mov_b32 s24, s33
	s_branch .Lf_960
